# in-proj GEMM: each XCD starts its 14 rounds at a different round (rotation), so the f32 K/V epilogue stores of different XCDs do not coincide
# speedup vs baseline: 1.0030x; 1.0030x over previous
.LBB0_771:
	v_add_u32_e32 v0, s76, v8
	s_cmpk_lt_i32 s78, 0xe00
	v_writelane_b32 v255, s80, 1
	v_readfirstlane_b32 s18, v0
	s_cselect_b64 s[40:41], -1, 0
	s_cmpk_gt_i32 s78, 0xdff
	v_mbcnt_lo_u32_b32 v0, -1, 0
	v_mbcnt_hi_u32_b32 v0, -1, v0
	s_cbranch_scc1 .LBB0_773
	s_and_b32 s5, s78, 7
	s_lshl_b32 s5, s5, 8
	s_add_i32 s5, s5, s78
	s_ashr_i32 s0, s5, 31
	s_lshr_b32 s0, s0, 29
	s_add_i32 s0, s5, s0
	s_ashr_i32 s1, s0, 3
	s_and_b32 s0, s0, -8
	s_sub_i32 s0, s5, s0
	s_cmp_lt_i32 s0, 0
	s_movk_i32 s4, 0x1c1
	s_cselect_b32 s4, s4, 0x1c0
	s_mul_i32 s0, s0, s4
	s_add_i32 s0, s0, s1
	s_mul_hi_i32 s1, s0, 0x92492493
	s_add_i32 s1, s1, s0
	s_lshr_b32 s4, s1, 31
	s_ashr_i32 s1, s1, 6
	s_add_i32 s1, s1, s4
	s_lshl_b32 s4, s1, 3
	s_mulk_i32 s1, 0x70
	s_sub_i32 s0, s0, s1
	s_bfe_i32 s1, s0, 0x80000
	s_bfe_u32 s1, s1, 0x3000c
	s_add_i32 s1, s0, s1
	s_bfe_i32 s5, s1, 0x80000
	s_and_b32 s1, s1, 0xf8
	s_sub_i32 s0, s0, s1
	s_sext_i32_i16 s5, s5
	s_sext_i32_i8 s0, s0
	s_add_i32 s4, s4, s0
	s_ashr_i32 s8, s5, 3

.LBB0_781:
	s_add_i32 s18, s5, 1
	s_and_b32 s9, s78, 7
	s_add_i32 s9, s9, s18
	s_cmp_ge_i32 s9, 14
	s_cselect_b32 s19, 14, 0
	s_sub_i32 s9, s9, s19
	s_mul_i32 s36, s9, s79
	s_add_u32 s36, s36, s78
	s_mov_b32 s37, 0
	s_cmp_lt_i32 s18, 14
	s_cselect_b64 s[38:39], -1, 0
	s_cselect_b64 vcc, 0, -1
	s_cbranch_vccnz .LBB0_783
	s_ashr_i32 s9, s36, 31
	s_lshr_b32 s9, s9, 29
	s_add_i32 s9, s36, s9
	s_ashr_i32 s19, s9, 3
	s_and_b32 s9, s9, -8
	s_sub_i32 s9, s36, s9
	s_cmp_lt_i32 s9, 0
	s_movk_i32 s36, 0x1c1
	s_cselect_b32 s36, s36, 0x1c0
	s_mul_i32 s9, s9, s36
	s_add_i32 s9, s9, s19
	s_mul_hi_i32 s19, s9, 0x92492493
	s_add_i32 s19, s19, s9
	s_lshr_b32 s36, s19, 31
	s_ashr_i32 s19, s19, 6
	s_add_i32 s19, s19, s36
	s_lshl_b32 s36, s19, 3
	s_sub_i32 s37, 0x100, s36
	s_min_i32 s37, s37, 8
	s_abs_i32 s42, s37
	v_cvt_f32_u32_e32 v0, s42
	s_sub_i32 s68, 0, s42
	s_mulk_i32 s19, 0x70
	s_sub_i32 s9, s9, s19
	v_rcp_iflag_f32_e32 v0, v0
	s_abs_i32 s19, s9
	s_xor_b32 s43, s9, s37
	s_ashr_i32 s43, s43, 31
	v_mul_f32_e32 v0, 0x4f7ffffe, v0
	v_cvt_u32_f32_e32 v0, v0
	s_nop 0
	v_readfirstlane_b32 s69, v0
	s_mul_i32 s68, s68, s69
	s_mul_hi_u32 s68, s69, s68
	s_add_i32 s69, s69, s68
	s_mul_hi_u32 s68, s19, s69
	s_mul_i32 s69, s68, s42
	s_sub_i32 s19, s19, s69
	s_add_i32 s70, s68, 1
	s_sub_i32 s69, s19, s42
	s_cmp_ge_u32 s19, s42
	s_cselect_b32 s68, s70, s68
	s_cselect_b32 s19, s69, s19
	s_add_i32 s69, s68, 1
	s_cmp_ge_u32 s19, s42
	s_cselect_b32 s19, s69, s68
	s_xor_b32 s19, s19, s43
	s_sub_i32 s68, s19, s43
	s_mul_i32 s19, s68, s37
	s_sub_i32 s9, s9, s19
	s_add_i32 s70, s36, s9
